# attention item epilogue: the eight gate-row loads issued together at loop exit instead of one per chunk behind a full vmcnt(0)
# speedup vs baseline: 1.0056x; 1.0021x over previous
.LBB0_40:
	s_setprio 0
	ds_bpermute_b32 v66, v214, v224
	s_add_u32 s4, s4, s40
	s_addc_u32 s5, 0, s41
	v_lshl_add_u64 v[204:205], s[4:5], 0, v[196:197]
	s_lshl_b32 s13, s10, 8
	s_and_b32 s13, s13, 0x700
	v_lshlrev_b64 v[204:205], 12, v[204:205]
	v_or_b32_e32 v204, s13, v204
	v_lshl_add_u64 v[204:205], v[202:203], 0, v[204:205]
	v_lshl_add_u64 v[204:205], v[204:205], 0, s[0:1]
	s_mov_b64 s[66:67], 0x219b000
	v_lshl_add_u64 v[204:205], v[204:205], 0, s[66:67]
	s_mov_b64 s[66:67], 0x20000
	global_load_dwordx4 v[98:101], v[204:205], off offset:1536
	v_lshl_add_u64 v[204:205], v[204:205], 0, s[66:67]
	global_load_dwordx4 v[102:105], v[204:205], off offset:1536
	v_lshl_add_u64 v[204:205], v[204:205], 0, s[66:67]
	global_load_dwordx4 v[106:109], v[204:205], off offset:1536
	v_lshl_add_u64 v[204:205], v[204:205], 0, s[66:67]
	global_load_dwordx4 v[110:113], v[204:205], off offset:1536
	v_lshl_add_u64 v[204:205], v[204:205], 0, s[66:67]
	global_load_dwordx4 v[114:117], v[204:205], off offset:1536
	v_lshl_add_u64 v[204:205], v[204:205], 0, s[66:67]
	global_load_dwordx4 v[118:121], v[204:205], off offset:1536
	v_lshl_add_u64 v[204:205], v[204:205], 0, s[66:67]
	global_load_dwordx4 v[122:125], v[204:205], off offset:1536
	v_lshl_add_u64 v[204:205], v[204:205], 0, s[66:67]
	global_load_dwordx4 v[126:129], v[204:205], off offset:1536
	s_mov_b64 s[16:17], 0x80000
	s_waitcnt lgkmcnt(0)
	v_add_f32_e32 v66, v224, v66
	v_div_scale_f32 v67, s[14:15], v66, v66, 1.0
	v_rcp_f32_e32 v68, v67
	v_div_scale_f32 v69, vcc, 1.0, v66, 1.0
	s_mov_b64 s[14:15], 0x40000
	v_fma_f32 v70, -v67, v68, 1.0
	v_fmac_f32_e32 v68, v70, v68
	v_mul_f32_e32 v70, v69, v68
	v_fma_f32 v71, -v67, v70, v69
	v_fmac_f32_e32 v70, v71, v68
	v_fma_f32 v67, -v67, v70, v69
	v_div_fmas_f32 v67, v67, v68, v70
	v_div_fixup_f32 v66, v67, v66, 1.0
	v_mul_f32_e32 v67, v51, v66
	v_mul_f32_e32 v51, v52, v66
	v_mul_f32_e32 v52, v53, v66
	v_mul_f32_e32 v50, v50, v66
	v_cvt_pk_bf16_f32 v51, v51, v52
	v_mul_f32_e32 v52, v54, v66
	v_mul_f32_e32 v54, v55, v66
	v_mul_f32_e32 v53, v56, v66
	v_mul_f32_e32 v55, v57, v66
	v_cvt_pk_bf16_f32 v50, v50, v67
	v_cvt_pk_bf16_f32 v53, v53, v55
	v_cvt_pk_bf16_f32 v52, v52, v54
	ds_write2_b64 v218, v[50:51], v[52:53] offset1:2
	v_mul_f32_e32 v50, v58, v66
	v_mul_f32_e32 v52, v59, v66
	v_mul_f32_e32 v51, v60, v66
	v_mul_f32_e32 v53, v61, v66
	v_cvt_pk_bf16_f32 v51, v51, v53
	v_cvt_pk_bf16_f32 v50, v50, v52
	v_mul_f32_e32 v52, v62, v66
	v_mul_f32_e32 v54, v63, v66
	v_mul_f32_e32 v53, v64, v66
	v_mul_f32_e32 v55, v65, v66
	v_cvt_pk_bf16_f32 v53, v53, v55
	v_cvt_pk_bf16_f32 v52, v52, v54
	ds_write2_b64 v218, v[50:51], v[52:53] offset0:4 offset1:6
	v_mul_f32_e32 v50, v35, v66
	v_mul_f32_e32 v35, v36, v66
	v_mul_f32_e32 v36, v37, v66
	v_mul_f32_e32 v34, v34, v66
	v_cvt_pk_bf16_f32 v35, v35, v36
	v_mul_f32_e32 v36, v38, v66
	v_mul_f32_e32 v38, v39, v66
	v_mul_f32_e32 v37, v40, v66
	v_mul_f32_e32 v39, v41, v66
	v_cvt_pk_bf16_f32 v34, v34, v50
	v_cvt_pk_bf16_f32 v37, v37, v39
	v_cvt_pk_bf16_f32 v36, v36, v38
	ds_write2_b64 v218, v[34:35], v[36:37] offset0:8 offset1:10
	v_mul_f32_e32 v34, v42, v66
	v_mul_f32_e32 v36, v43, v66
	v_mul_f32_e32 v35, v44, v66
	v_mul_f32_e32 v37, v45, v66
	v_cvt_pk_bf16_f32 v35, v35, v37
	v_cvt_pk_bf16_f32 v34, v34, v36
	v_mul_f32_e32 v36, v46, v66
	v_mul_f32_e32 v38, v47, v66
	v_mul_f32_e32 v37, v48, v66
	v_mul_f32_e32 v39, v49, v66
	v_cvt_pk_bf16_f32 v37, v37, v39
	v_cvt_pk_bf16_f32 v36, v36, v38
	ds_write2_b64 v218, v[34:35], v[36:37] offset0:12 offset1:14
	v_mul_f32_e32 v34, v19, v66
	v_mul_f32_e32 v19, v20, v66
	v_mul_f32_e32 v20, v21, v66
	v_mul_f32_e32 v18, v18, v66
	v_cvt_pk_bf16_f32 v19, v19, v20
	v_mul_f32_e32 v20, v22, v66
	v_mul_f32_e32 v22, v23, v66
	v_mul_f32_e32 v21, v24, v66
	v_mul_f32_e32 v23, v25, v66
	v_cvt_pk_bf16_f32 v18, v18, v34
	v_cvt_pk_bf16_f32 v21, v21, v23
	v_cvt_pk_bf16_f32 v20, v20, v22
	ds_write2_b64 v218, v[18:19], v[20:21] offset0:16 offset1:18
	v_mul_f32_e32 v18, v26, v66
	v_mul_f32_e32 v20, v27, v66
	v_mul_f32_e32 v19, v28, v66
	v_mul_f32_e32 v21, v29, v66
	v_cvt_pk_bf16_f32 v19, v19, v21
	v_cvt_pk_bf16_f32 v18, v18, v20
	v_mul_f32_e32 v20, v30, v66
	v_mul_f32_e32 v22, v31, v66
	v_mul_f32_e32 v21, v32, v66
	v_mul_f32_e32 v23, v33, v66
	v_cvt_pk_bf16_f32 v21, v21, v23
	v_cvt_pk_bf16_f32 v20, v20, v22
	ds_write2_b64 v218, v[18:19], v[20:21] offset0:20 offset1:22
	v_mul_f32_e32 v18, v3, v66
	v_mul_f32_e32 v3, v4, v66
	v_mul_f32_e32 v4, v5, v66
	v_mul_f32_e32 v2, v2, v66
	v_cvt_pk_bf16_f32 v3, v3, v4
	v_mul_f32_e32 v4, v6, v66
	v_mul_f32_e32 v6, v7, v66
	v_mul_f32_e32 v5, v8, v66
	v_mul_f32_e32 v7, v9, v66
	v_cvt_pk_bf16_f32 v2, v2, v18
	v_cvt_pk_bf16_f32 v5, v5, v7
	v_cvt_pk_bf16_f32 v4, v4, v6
	ds_write2_b64 v218, v[2:3], v[4:5] offset0:24 offset1:26
	v_mul_f32_e32 v2, v10, v66
	v_mul_f32_e32 v4, v11, v66
	v_mul_f32_e32 v3, v12, v66
	v_mul_f32_e32 v5, v13, v66
	v_cvt_pk_bf16_f32 v3, v3, v5
	v_cvt_pk_bf16_f32 v2, v2, v4
	v_mul_f32_e32 v4, v14, v66
	v_mul_f32_e32 v6, v15, v66
	v_mul_f32_e32 v5, v16, v66
	v_mul_f32_e32 v7, v17, v66
	v_cvt_pk_bf16_f32 v5, v5, v7
	v_cvt_pk_bf16_f32 v4, v4, v6
	ds_write2_b64 v218, v[2:3], v[4:5] offset0:28 offset1:30
	v_lshl_add_u64 v[2:3], s[4:5], 0, v[196:197]
	s_lshl_b32 s4, s10, 8
	v_lshlrev_b64 v[4:5], 11, v[2:3]
	s_and_b32 s4, s4, 0x700
	v_lshlrev_b64 v[2:3], 12, v[2:3]
	v_or_b32_e32 v4, s4, v4
	v_or_b32_e32 v2, s4, v2
	v_lshl_add_u64 v[6:7], v[202:203], 0, v[4:5]
	v_lshl_add_u64 v[8:9], v[202:203], 0, v[2:3]
	s_mov_b32 s4, 0
	s_waitcnt lgkmcnt(0)
	s_barrier
.LBB0_41:
	v_lshl_add_u64 v[10:11], v[8:9], 0, s[0:1]
	v_add_co_u32_e32 v12, vcc, 0x219b000, v10
	v_add_u32_e32 v14, s4, v189
	s_nop 0
	v_addc_co_u32_e32 v13, vcc, 0, v11, vcc
	s_waitcnt vmcnt(7)
	v_mov_b64_e32 v[16:17], v[98:99]
	v_mov_b64_e32 v[18:19], v[100:101]
	ds_read_b128 v[2:5], v14
	s_mov_b32 s5, 0x3739b000
	s_add_i32 s4, s4, 0x8800
	v_lshl_add_u64 v[8:9], v[8:9], 0, s[16:17]
	s_cmp_eq_u32 s4, 0x11000
	s_waitcnt lgkmcnt(0)
	v_lshlrev_b32_e32 v12, 16, v2
	v_and_b32_e32 v13, 0xffff0000, v2
	s_waitcnt vmcnt(7)
	v_lshlrev_b32_e32 v15, 16, v16
	v_and_b32_e32 v2, 0xffff0000, v16
	v_mul_f32_e32 v16, 0xbfb8aa3b, v15
	v_exp_f32_e32 v20, v16
	v_mul_f32_e32 v16, 0xbfb8aa3b, v2
	v_exp_f32_e32 v21, v16
	s_nop 0
	v_pk_add_f32 v[20:21], v[20:21], 1.0 op_sel_hi:[1,0]
	s_nop 0
	v_div_scale_f32 v16, s[10:11], v21, v21, v2
	v_rcp_f32_e32 v22, v16
	s_nop 0
	v_fma_f32 v23, -v16, v22, 1.0
	v_fmac_f32_e32 v22, v23, v22
	v_div_scale_f32 v23, vcc, v2, v21, v2
	v_mul_f32_e32 v24, v23, v22
	v_fma_f32 v25, -v16, v24, v23
	v_fmac_f32_e32 v24, v25, v22
	v_fma_f32 v16, -v16, v24, v23
	v_div_fmas_f32 v16, v16, v22, v24
	v_div_fixup_f32 v21, v16, v21, v2
	v_div_scale_f32 v2, s[10:11], v20, v20, v15
	v_rcp_f32_e32 v16, v2
	s_nop 0
	v_fma_f32 v22, -v2, v16, 1.0
	v_fmac_f32_e32 v16, v22, v16
	v_div_scale_f32 v22, vcc, v15, v20, v15
	v_mul_f32_e32 v23, v22, v16
	v_fma_f32 v24, -v2, v23, v22
	v_fmac_f32_e32 v23, v24, v16
	v_fma_f32 v2, -v2, v23, v22
	v_div_fmas_f32 v2, v2, v16, v23
	v_div_fixup_f32 v20, v2, v20, v15
	v_pk_mul_f32 v[12:13], v[20:21], v[12:13]
	v_lshlrev_b32_e32 v15, 16, v17
	v_cvt_pk_bf16_f32 v2, v12, v13
	v_lshlrev_b32_e32 v12, 16, v3
	v_and_b32_e32 v13, 0xffff0000, v3
	v_and_b32_e32 v3, 0xffff0000, v17
	v_mul_f32_e32 v16, 0xbfb8aa3b, v15
	v_mul_f32_e32 v17, 0xbfb8aa3b, v3
	v_exp_f32_e32 v16, v16
	v_exp_f32_e32 v17, v17
	s_nop 0
	v_pk_add_f32 v[16:17], v[16:17], 1.0 op_sel_hi:[1,0]
	s_nop 0
	v_div_scale_f32 v20, s[10:11], v17, v17, v3
	v_rcp_f32_e32 v21, v20
	s_nop 0
	v_fma_f32 v22, -v20, v21, 1.0
	v_fmac_f32_e32 v21, v22, v21
	v_div_scale_f32 v22, vcc, v3, v17, v3
	v_mul_f32_e32 v23, v22, v21
	v_fma_f32 v24, -v20, v23, v22
	v_fmac_f32_e32 v23, v24, v21
	v_fma_f32 v20, -v20, v23, v22
	v_div_fmas_f32 v20, v20, v21, v23
	v_div_fixup_f32 v17, v20, v17, v3
	v_div_scale_f32 v3, s[10:11], v16, v16, v15
	v_rcp_f32_e32 v20, v3
	s_nop 0
	v_fma_f32 v21, -v3, v20, 1.0
	v_fmac_f32_e32 v20, v21, v20
	v_div_scale_f32 v21, vcc, v15, v16, v15
	v_mul_f32_e32 v22, v21, v20
	v_fma_f32 v23, -v3, v22, v21
	v_fmac_f32_e32 v22, v23, v20
	v_fma_f32 v3, -v3, v22, v21
	v_div_fmas_f32 v3, v3, v20, v22
	v_div_fixup_f32 v16, v3, v16, v15
	v_pk_mul_f32 v[12:13], v[16:17], v[12:13]
	v_lshlrev_b32_e32 v15, 16, v18
	v_cvt_pk_bf16_f32 v3, v12, v13
	v_lshlrev_b32_e32 v12, 16, v4
	v_and_b32_e32 v13, 0xffff0000, v4
	v_and_b32_e32 v4, 0xffff0000, v18
	v_mul_f32_e32 v16, 0xbfb8aa3b, v15
	v_mul_f32_e32 v17, 0xbfb8aa3b, v4
	v_exp_f32_e32 v16, v16
	v_exp_f32_e32 v17, v17
	s_nop 0
	v_pk_add_f32 v[16:17], v[16:17], 1.0 op_sel_hi:[1,0]
	s_nop 0
	v_div_scale_f32 v18, s[10:11], v17, v17, v4
	v_rcp_f32_e32 v20, v18
	s_nop 0
	v_fma_f32 v21, -v18, v20, 1.0
	v_fmac_f32_e32 v20, v21, v20
	v_div_scale_f32 v21, vcc, v4, v17, v4
	v_mul_f32_e32 v22, v21, v20
	v_fma_f32 v23, -v18, v22, v21
	v_fmac_f32_e32 v22, v23, v20
	v_fma_f32 v18, -v18, v22, v21
	v_div_fmas_f32 v18, v18, v20, v22
	v_div_fixup_f32 v17, v18, v17, v4
	v_div_scale_f32 v4, s[10:11], v16, v16, v15
	v_rcp_f32_e32 v18, v4
	s_nop 0
	v_fma_f32 v20, -v4, v18, 1.0
	v_fmac_f32_e32 v18, v20, v18
	v_div_scale_f32 v20, vcc, v15, v16, v15
	v_mul_f32_e32 v21, v20, v18
	v_fma_f32 v22, -v4, v21, v20
	v_fmac_f32_e32 v21, v22, v18
	v_fma_f32 v4, -v4, v21, v20
	v_div_fmas_f32 v4, v4, v18, v21
	v_div_fixup_f32 v16, v4, v16, v15
	v_pk_mul_f32 v[12:13], v[16:17], v[12:13]
	v_lshlrev_b32_e32 v15, 16, v19
	v_cvt_pk_bf16_f32 v4, v12, v13
	v_lshlrev_b32_e32 v12, 16, v5
	v_and_b32_e32 v13, 0xffff0000, v5
	v_and_b32_e32 v5, 0xffff0000, v19
	v_mul_f32_e32 v16, 0xbfb8aa3b, v15
	v_mul_f32_e32 v17, 0xbfb8aa3b, v5
	v_exp_f32_e32 v16, v16
	v_exp_f32_e32 v17, v17
	s_nop 0
	v_pk_add_f32 v[16:17], v[16:17], 1.0 op_sel_hi:[1,0]
	s_nop 0
	v_div_scale_f32 v18, s[10:11], v17, v17, v5
	v_rcp_f32_e32 v19, v18
	s_nop 0
	v_fma_f32 v20, -v18, v19, 1.0
	v_fmac_f32_e32 v19, v20, v19
	v_div_scale_f32 v20, vcc, v5, v17, v5
	v_mul_f32_e32 v21, v20, v19
	v_fma_f32 v22, -v18, v21, v20
	v_fmac_f32_e32 v21, v22, v19
	v_fma_f32 v18, -v18, v21, v20
	v_div_fmas_f32 v18, v18, v19, v21
	v_div_fixup_f32 v17, v18, v17, v5
	v_div_scale_f32 v5, s[10:11], v16, v16, v15
	v_rcp_f32_e32 v18, v5
	s_nop 0
	v_fma_f32 v19, -v5, v18, 1.0
	v_fmac_f32_e32 v18, v19, v18
	v_div_scale_f32 v19, vcc, v15, v16, v15
	v_mul_f32_e32 v20, v19, v18
	v_fma_f32 v21, -v5, v20, v19
	v_fmac_f32_e32 v20, v21, v18
	v_fma_f32 v5, -v5, v20, v19
	v_div_fmas_f32 v5, v5, v18, v20
	v_div_fixup_f32 v16, v5, v16, v15
	v_pk_mul_f32 v[12:13], v[16:17], v[12:13]
	s_nop 0
	v_cvt_pk_bf16_f32 v5, v12, v13
	v_lshl_add_u64 v[12:13], v[6:7], 0, s[0:1]
	v_add_co_u32_e32 v16, vcc, s5, v12
	s_mov_b32 s5, 0x21bb000
	s_nop 0
	v_addc_co_u32_e32 v17, vcc, 0, v13, vcc
	global_store_dwordx4 v[16:17], v[2:5], off offset:1536
	v_add_co_u32_e32 v16, vcc, s5, v10
	ds_read_b128 v[2:5], v14 offset:8704
	s_nop 0
	v_addc_co_u32_e32 v17, vcc, 0, v11, vcc
	s_waitcnt vmcnt(7)
	v_mov_b64_e32 v[16:17], v[102:103]
	v_mov_b64_e32 v[18:19], v[104:105]
	s_mov_b32 s5, 0x373ab000
	s_waitcnt lgkmcnt(0)
	v_lshlrev_b32_e32 v20, 16, v2
	v_and_b32_e32 v21, 0xffff0000, v2
	v_lshl_add_u64 v[6:7], v[6:7], 0, s[14:15]
	s_waitcnt vmcnt(7)
	v_lshlrev_b32_e32 v15, 16, v16
	v_and_b32_e32 v2, 0xffff0000, v16
	v_mul_f32_e32 v16, 0xbfb8aa3b, v15
	v_exp_f32_e32 v22, v16
	v_mul_f32_e32 v16, 0xbfb8aa3b, v2
	v_exp_f32_e32 v23, v16
	s_nop 0
	v_pk_add_f32 v[22:23], v[22:23], 1.0 op_sel_hi:[1,0]
	s_nop 0
	v_div_scale_f32 v16, s[10:11], v23, v23, v2
	v_rcp_f32_e32 v24, v16
	s_nop 0
	v_fma_f32 v25, -v16, v24, 1.0
	v_fmac_f32_e32 v24, v25, v24
	v_div_scale_f32 v25, vcc, v2, v23, v2
	v_mul_f32_e32 v26, v25, v24
	v_fma_f32 v27, -v16, v26, v25
	v_fmac_f32_e32 v26, v27, v24
	v_fma_f32 v16, -v16, v26, v25
	v_div_fmas_f32 v16, v16, v24, v26
	v_div_fixup_f32 v23, v16, v23, v2
	v_div_scale_f32 v2, s[10:11], v22, v22, v15
	v_rcp_f32_e32 v16, v2
	s_nop 0
	v_fma_f32 v24, -v2, v16, 1.0
	v_fmac_f32_e32 v16, v24, v16
	v_div_scale_f32 v24, vcc, v15, v22, v15
	v_mul_f32_e32 v25, v24, v16
	v_fma_f32 v26, -v2, v25, v24
	v_fmac_f32_e32 v25, v26, v16
	v_fma_f32 v2, -v2, v25, v24
	v_div_fmas_f32 v2, v2, v16, v25
	v_div_fixup_f32 v22, v2, v22, v15
	v_pk_mul_f32 v[20:21], v[22:23], v[20:21]
	v_lshlrev_b32_e32 v15, 16, v17
	v_cvt_pk_bf16_f32 v2, v20, v21
	v_lshlrev_b32_e32 v20, 16, v3
	v_and_b32_e32 v21, 0xffff0000, v3
	v_and_b32_e32 v3, 0xffff0000, v17
	v_mul_f32_e32 v16, 0xbfb8aa3b, v15
	v_mul_f32_e32 v17, 0xbfb8aa3b, v3
	v_exp_f32_e32 v16, v16
	v_exp_f32_e32 v17, v17
	s_nop 0
	v_pk_add_f32 v[16:17], v[16:17], 1.0 op_sel_hi:[1,0]
	s_nop 0
	v_div_scale_f32 v22, s[10:11], v17, v17, v3
	v_rcp_f32_e32 v23, v22
	s_nop 0
	v_fma_f32 v24, -v22, v23, 1.0
	v_fmac_f32_e32 v23, v24, v23
	v_div_scale_f32 v24, vcc, v3, v17, v3
	v_mul_f32_e32 v25, v24, v23
	v_fma_f32 v26, -v22, v25, v24
	v_fmac_f32_e32 v25, v26, v23
	v_fma_f32 v22, -v22, v25, v24
	v_div_fmas_f32 v22, v22, v23, v25
	v_div_fixup_f32 v17, v22, v17, v3
	v_div_scale_f32 v3, s[10:11], v16, v16, v15
	v_rcp_f32_e32 v22, v3
	s_nop 0
	v_fma_f32 v23, -v3, v22, 1.0
	v_fmac_f32_e32 v22, v23, v22
	v_div_scale_f32 v23, vcc, v15, v16, v15
	v_mul_f32_e32 v24, v23, v22
	v_fma_f32 v25, -v3, v24, v23
	v_fmac_f32_e32 v24, v25, v22
	v_fma_f32 v3, -v3, v24, v23
	v_div_fmas_f32 v3, v3, v22, v24
	v_div_fixup_f32 v16, v3, v16, v15
	v_pk_mul_f32 v[16:17], v[16:17], v[20:21]
	v_lshlrev_b32_e32 v15, 16, v18
	v_cvt_pk_bf16_f32 v3, v16, v17
	v_lshlrev_b32_e32 v16, 16, v4
	v_and_b32_e32 v17, 0xffff0000, v4
	v_and_b32_e32 v4, 0xffff0000, v18
	v_mul_f32_e32 v18, 0xbfb8aa3b, v15
	v_exp_f32_e32 v20, v18
	v_mul_f32_e32 v18, 0xbfb8aa3b, v4
	v_exp_f32_e32 v21, v18
	s_nop 0
	v_pk_add_f32 v[20:21], v[20:21], 1.0 op_sel_hi:[1,0]
	s_nop 0
	v_div_scale_f32 v18, s[10:11], v21, v21, v4
	v_rcp_f32_e32 v22, v18
	s_nop 0
	v_fma_f32 v23, -v18, v22, 1.0
	v_fmac_f32_e32 v22, v23, v22
	v_div_scale_f32 v23, vcc, v4, v21, v4
	v_mul_f32_e32 v24, v23, v22
	v_fma_f32 v25, -v18, v24, v23
	v_fmac_f32_e32 v24, v25, v22
	v_fma_f32 v18, -v18, v24, v23
	v_div_fmas_f32 v18, v18, v22, v24
	v_div_fixup_f32 v21, v18, v21, v4
	v_div_scale_f32 v4, s[10:11], v20, v20, v15
	v_rcp_f32_e32 v18, v4
	s_nop 0
	v_fma_f32 v22, -v4, v18, 1.0
	v_fmac_f32_e32 v18, v22, v18
	v_div_scale_f32 v22, vcc, v15, v20, v15
	v_mul_f32_e32 v23, v22, v18
	v_fma_f32 v24, -v4, v23, v22
	v_fmac_f32_e32 v23, v24, v18
	v_fma_f32 v4, -v4, v23, v22
	v_div_fmas_f32 v4, v4, v18, v23
	v_div_fixup_f32 v20, v4, v20, v15
	v_pk_mul_f32 v[16:17], v[20:21], v[16:17]
	v_lshlrev_b32_e32 v15, 16, v19
	v_cvt_pk_bf16_f32 v4, v16, v17
	v_lshlrev_b32_e32 v16, 16, v5
	v_and_b32_e32 v17, 0xffff0000, v5
	v_and_b32_e32 v5, 0xffff0000, v19
	v_mul_f32_e32 v18, 0xbfb8aa3b, v15
	v_mul_f32_e32 v19, 0xbfb8aa3b, v5
	v_exp_f32_e32 v18, v18
	v_exp_f32_e32 v19, v19
	s_nop 0
	v_pk_add_f32 v[18:19], v[18:19], 1.0 op_sel_hi:[1,0]
	s_nop 0
	v_div_scale_f32 v20, s[10:11], v19, v19, v5
	v_rcp_f32_e32 v21, v20
	s_nop 0
	v_fma_f32 v22, -v20, v21, 1.0
	v_fmac_f32_e32 v21, v22, v21
	v_div_scale_f32 v22, vcc, v5, v19, v5
	v_mul_f32_e32 v23, v22, v21
	v_fma_f32 v24, -v20, v23, v22
	v_fmac_f32_e32 v23, v24, v21
	v_fma_f32 v20, -v20, v23, v22
	v_div_fmas_f32 v20, v20, v21, v23
	v_div_fixup_f32 v19, v20, v19, v5
	v_div_scale_f32 v5, s[10:11], v18, v18, v15
	v_rcp_f32_e32 v20, v5
	s_nop 0
	v_fma_f32 v21, -v5, v20, 1.0
	v_fmac_f32_e32 v20, v21, v20
	v_div_scale_f32 v21, vcc, v15, v18, v15
	v_mul_f32_e32 v22, v21, v20
	v_fma_f32 v23, -v5, v22, v21
	v_fmac_f32_e32 v22, v23, v20
	v_fma_f32 v5, -v5, v22, v21
	v_div_fmas_f32 v5, v5, v20, v22
	v_div_fixup_f32 v18, v5, v18, v15
	v_pk_mul_f32 v[16:17], v[18:19], v[16:17]
	s_nop 0
	v_cvt_pk_bf16_f32 v5, v16, v17
	v_add_co_u32_e32 v16, vcc, s5, v12
	s_mov_b32 s5, 0x21db000
	s_nop 0
	v_addc_co_u32_e32 v17, vcc, 0, v13, vcc
	global_store_dwordx4 v[16:17], v[2:5], off offset:1536
	v_add_co_u32_e32 v16, vcc, s5, v10
	ds_read_b128 v[2:5], v14 offset:17408
	s_nop 0
	v_addc_co_u32_e32 v17, vcc, 0, v11, vcc
	s_waitcnt vmcnt(7)
	v_mov_b64_e32 v[16:17], v[106:107]
	v_mov_b64_e32 v[18:19], v[108:109]
	s_mov_b32 s5, 0x373bb000
	s_waitcnt lgkmcnt(0)
	v_lshlrev_b32_e32 v20, 16, v2
	v_and_b32_e32 v21, 0xffff0000, v2
	s_waitcnt vmcnt(7)
	v_lshlrev_b32_e32 v15, 16, v16
	v_and_b32_e32 v2, 0xffff0000, v16
	v_mul_f32_e32 v16, 0xbfb8aa3b, v15
	v_exp_f32_e32 v22, v16
	v_mul_f32_e32 v16, 0xbfb8aa3b, v2
	v_exp_f32_e32 v23, v16
	s_nop 0
	v_pk_add_f32 v[22:23], v[22:23], 1.0 op_sel_hi:[1,0]
	s_nop 0
	v_div_scale_f32 v16, s[10:11], v23, v23, v2
	v_rcp_f32_e32 v24, v16
	s_nop 0
	v_fma_f32 v25, -v16, v24, 1.0
	v_fmac_f32_e32 v24, v25, v24
	v_div_scale_f32 v25, vcc, v2, v23, v2
	v_mul_f32_e32 v26, v25, v24
	v_fma_f32 v27, -v16, v26, v25
	v_fmac_f32_e32 v26, v27, v24
	v_fma_f32 v16, -v16, v26, v25
	v_div_fmas_f32 v16, v16, v24, v26
	v_div_fixup_f32 v23, v16, v23, v2
	v_div_scale_f32 v2, s[10:11], v22, v22, v15
	v_rcp_f32_e32 v16, v2
	s_nop 0
	v_fma_f32 v24, -v2, v16, 1.0
	v_fmac_f32_e32 v16, v24, v16
	v_div_scale_f32 v24, vcc, v15, v22, v15
	v_mul_f32_e32 v25, v24, v16
	v_fma_f32 v26, -v2, v25, v24
	v_fmac_f32_e32 v25, v26, v16
	v_fma_f32 v2, -v2, v25, v24
	v_div_fmas_f32 v2, v2, v16, v25
	v_div_fixup_f32 v22, v2, v22, v15
	v_pk_mul_f32 v[20:21], v[22:23], v[20:21]
	v_lshlrev_b32_e32 v15, 16, v17
	v_cvt_pk_bf16_f32 v2, v20, v21
	v_lshlrev_b32_e32 v20, 16, v3
	v_and_b32_e32 v21, 0xffff0000, v3
	v_and_b32_e32 v3, 0xffff0000, v17
	v_mul_f32_e32 v16, 0xbfb8aa3b, v15
	v_mul_f32_e32 v17, 0xbfb8aa3b, v3
	v_exp_f32_e32 v16, v16
	v_exp_f32_e32 v17, v17
	s_nop 0
	v_pk_add_f32 v[16:17], v[16:17], 1.0 op_sel_hi:[1,0]
	s_nop 0
	v_div_scale_f32 v22, s[10:11], v17, v17, v3
	v_rcp_f32_e32 v23, v22
	s_nop 0
	v_fma_f32 v24, -v22, v23, 1.0
	v_fmac_f32_e32 v23, v24, v23
	v_div_scale_f32 v24, vcc, v3, v17, v3
	v_mul_f32_e32 v25, v24, v23
	v_fma_f32 v26, -v22, v25, v24
	v_fmac_f32_e32 v25, v26, v23
	v_fma_f32 v22, -v22, v25, v24
	v_div_fmas_f32 v22, v22, v23, v25
	v_div_fixup_f32 v17, v22, v17, v3
	v_div_scale_f32 v3, s[10:11], v16, v16, v15
	v_rcp_f32_e32 v22, v3
	s_nop 0
	v_fma_f32 v23, -v3, v22, 1.0
	v_fmac_f32_e32 v22, v23, v22
	v_div_scale_f32 v23, vcc, v15, v16, v15
	v_mul_f32_e32 v24, v23, v22
	v_fma_f32 v25, -v3, v24, v23
	v_fmac_f32_e32 v24, v25, v22
	v_fma_f32 v3, -v3, v24, v23
	v_div_fmas_f32 v3, v3, v22, v24
	v_div_fixup_f32 v16, v3, v16, v15
	v_pk_mul_f32 v[16:17], v[16:17], v[20:21]
	v_lshlrev_b32_e32 v15, 16, v18
	v_cvt_pk_bf16_f32 v3, v16, v17
	v_lshlrev_b32_e32 v16, 16, v4
	v_and_b32_e32 v17, 0xffff0000, v4
	v_and_b32_e32 v4, 0xffff0000, v18
	v_mul_f32_e32 v18, 0xbfb8aa3b, v15
	v_exp_f32_e32 v20, v18
	v_mul_f32_e32 v18, 0xbfb8aa3b, v4
	v_exp_f32_e32 v21, v18
	s_nop 0
	v_pk_add_f32 v[20:21], v[20:21], 1.0 op_sel_hi:[1,0]
	s_nop 0
	v_div_scale_f32 v18, s[10:11], v21, v21, v4
	v_rcp_f32_e32 v22, v18
	s_nop 0
	v_fma_f32 v23, -v18, v22, 1.0
	v_fmac_f32_e32 v22, v23, v22
	v_div_scale_f32 v23, vcc, v4, v21, v4
	v_mul_f32_e32 v24, v23, v22
	v_fma_f32 v25, -v18, v24, v23
	v_fmac_f32_e32 v24, v25, v22
	v_fma_f32 v18, -v18, v24, v23
	v_div_fmas_f32 v18, v18, v22, v24
	v_div_fixup_f32 v21, v18, v21, v4
	v_div_scale_f32 v4, s[10:11], v20, v20, v15
	v_rcp_f32_e32 v18, v4
	s_nop 0
	v_fma_f32 v22, -v4, v18, 1.0
	v_fmac_f32_e32 v18, v22, v18
	v_div_scale_f32 v22, vcc, v15, v20, v15
	v_mul_f32_e32 v23, v22, v18
	v_fma_f32 v24, -v4, v23, v22
	v_fmac_f32_e32 v23, v24, v18
	v_fma_f32 v4, -v4, v23, v22
	v_div_fmas_f32 v4, v4, v18, v23
	v_div_fixup_f32 v20, v4, v20, v15
	v_pk_mul_f32 v[16:17], v[20:21], v[16:17]
	v_lshlrev_b32_e32 v15, 16, v19
	v_cvt_pk_bf16_f32 v4, v16, v17
	v_lshlrev_b32_e32 v16, 16, v5
	v_and_b32_e32 v17, 0xffff0000, v5
	v_and_b32_e32 v5, 0xffff0000, v19
	v_mul_f32_e32 v18, 0xbfb8aa3b, v15
	v_mul_f32_e32 v19, 0xbfb8aa3b, v5
	v_exp_f32_e32 v18, v18
	v_exp_f32_e32 v19, v19
	s_nop 0
	v_pk_add_f32 v[18:19], v[18:19], 1.0 op_sel_hi:[1,0]
	s_nop 0
	v_div_scale_f32 v20, s[10:11], v19, v19, v5
	v_rcp_f32_e32 v21, v20
	s_nop 0
	v_fma_f32 v22, -v20, v21, 1.0
	v_fmac_f32_e32 v21, v22, v21
	v_div_scale_f32 v22, vcc, v5, v19, v5
	v_mul_f32_e32 v23, v22, v21
	v_fma_f32 v24, -v20, v23, v22
	v_fmac_f32_e32 v23, v24, v21
	v_fma_f32 v20, -v20, v23, v22
	v_div_fmas_f32 v20, v20, v21, v23
	v_div_fixup_f32 v19, v20, v19, v5
	v_div_scale_f32 v5, s[10:11], v18, v18, v15
	v_rcp_f32_e32 v20, v5
	s_nop 0
	v_fma_f32 v21, -v5, v20, 1.0
	v_fmac_f32_e32 v20, v21, v20
	v_div_scale_f32 v21, vcc, v15, v18, v15
	v_mul_f32_e32 v22, v21, v20
	v_fma_f32 v23, -v5, v22, v21
	v_fmac_f32_e32 v22, v23, v20
	v_fma_f32 v5, -v5, v22, v21
	v_div_fmas_f32 v5, v5, v20, v22
	v_div_fixup_f32 v18, v5, v18, v15
	v_pk_mul_f32 v[16:17], v[18:19], v[16:17]
	s_nop 0
	v_cvt_pk_bf16_f32 v5, v16, v17
	v_add_co_u32_e32 v16, vcc, s5, v12
	s_mov_b32 s5, 0x21fb000
	s_nop 0
	v_addc_co_u32_e32 v17, vcc, 0, v13, vcc
	v_add_co_u32_e32 v10, vcc, s5, v10
	global_store_dwordx4 v[16:17], v[2:5], off offset:1536
	s_nop 0
	v_addc_co_u32_e32 v11, vcc, 0, v11, vcc
	ds_read_b128 v[2:5], v14 offset:26112
	s_waitcnt vmcnt(7)
	v_mov_b64_e32 v[14:15], v[110:111]
	v_mov_b64_e32 v[16:17], v[112:113]
	s_waitcnt lgkmcnt(0)
	v_lshlrev_b32_e32 v10, 16, v2
	v_and_b32_e32 v11, 0xffff0000, v2
	s_waitcnt vmcnt(7)
	v_lshlrev_b32_e32 v20, 16, v14
	v_and_b32_e32 v2, 0xffff0000, v14
	v_mul_f32_e32 v14, 0xbfb8aa3b, v20
	v_exp_f32_e32 v18, v14
	v_mul_f32_e32 v14, 0xbfb8aa3b, v2
	v_exp_f32_e32 v19, v14
	s_nop 0
	v_pk_add_f32 v[18:19], v[18:19], 1.0 op_sel_hi:[1,0]
	s_nop 0
	v_div_scale_f32 v14, s[10:11], v19, v19, v2
	v_rcp_f32_e32 v21, v14
	s_nop 0
	v_fma_f32 v22, -v14, v21, 1.0
	v_fmac_f32_e32 v21, v22, v21
	v_div_scale_f32 v22, vcc, v2, v19, v2
	v_mul_f32_e32 v23, v22, v21
	v_fma_f32 v24, -v14, v23, v22
	v_fmac_f32_e32 v23, v24, v21
	v_fma_f32 v14, -v14, v23, v22
	v_div_fmas_f32 v14, v14, v21, v23
	v_div_fixup_f32 v19, v14, v19, v2
	v_div_scale_f32 v2, s[10:11], v18, v18, v20
	v_rcp_f32_e32 v14, v2
	s_nop 0
	v_fma_f32 v21, -v2, v14, 1.0
	v_fmac_f32_e32 v14, v21, v14
	v_div_scale_f32 v21, vcc, v20, v18, v20
	v_mul_f32_e32 v22, v21, v14
	v_fma_f32 v23, -v2, v22, v21
	v_fmac_f32_e32 v22, v23, v14
	v_fma_f32 v2, -v2, v22, v21
	v_div_fmas_f32 v2, v2, v14, v22
	v_div_fixup_f32 v18, v2, v18, v20
	v_pk_mul_f32 v[10:11], v[18:19], v[10:11]
	v_lshlrev_b32_e32 v18, 16, v15
	v_cvt_pk_bf16_f32 v2, v10, v11
	v_lshlrev_b32_e32 v10, 16, v3
	v_and_b32_e32 v11, 0xffff0000, v3
	v_and_b32_e32 v3, 0xffff0000, v15
	v_mul_f32_e32 v14, 0xbfb8aa3b, v18
	v_mul_f32_e32 v15, 0xbfb8aa3b, v3
	v_exp_f32_e32 v14, v14
	v_exp_f32_e32 v15, v15
	s_nop 0
	v_pk_add_f32 v[14:15], v[14:15], 1.0 op_sel_hi:[1,0]
	s_nop 0
	v_div_scale_f32 v19, s[10:11], v15, v15, v3
	v_rcp_f32_e32 v20, v19
	s_nop 0
	v_fma_f32 v21, -v19, v20, 1.0
	v_fmac_f32_e32 v20, v21, v20
	v_div_scale_f32 v21, vcc, v3, v15, v3
	v_mul_f32_e32 v22, v21, v20
	v_fma_f32 v23, -v19, v22, v21
	v_fmac_f32_e32 v22, v23, v20
	v_fma_f32 v19, -v19, v22, v21
	v_div_fmas_f32 v19, v19, v20, v22
	v_div_fixup_f32 v15, v19, v15, v3
	v_div_scale_f32 v3, s[10:11], v14, v14, v18
	v_rcp_f32_e32 v19, v3
	s_nop 0
	v_fma_f32 v20, -v3, v19, 1.0
	v_fmac_f32_e32 v19, v20, v19
	v_div_scale_f32 v20, vcc, v18, v14, v18
	v_mul_f32_e32 v21, v20, v19
	v_fma_f32 v22, -v3, v21, v20
	v_fmac_f32_e32 v21, v22, v19
	v_fma_f32 v3, -v3, v21, v20
	v_div_fmas_f32 v3, v3, v19, v21
	v_div_fixup_f32 v14, v3, v14, v18
	v_pk_mul_f32 v[10:11], v[14:15], v[10:11]
	v_lshlrev_b32_e32 v18, 16, v16
	v_cvt_pk_bf16_f32 v3, v10, v11
	v_lshlrev_b32_e32 v10, 16, v4
	v_and_b32_e32 v11, 0xffff0000, v4
	v_and_b32_e32 v4, 0xffff0000, v16
	v_mul_f32_e32 v14, 0xbfb8aa3b, v18
	v_mul_f32_e32 v15, 0xbfb8aa3b, v4
	v_exp_f32_e32 v14, v14
	v_exp_f32_e32 v15, v15
	s_nop 0
	v_pk_add_f32 v[14:15], v[14:15], 1.0 op_sel_hi:[1,0]
	s_nop 0
	v_div_scale_f32 v16, s[10:11], v15, v15, v4
	v_rcp_f32_e32 v19, v16
	s_nop 0
	v_fma_f32 v20, -v16, v19, 1.0
	v_fmac_f32_e32 v19, v20, v19
	v_div_scale_f32 v20, vcc, v4, v15, v4
	v_mul_f32_e32 v21, v20, v19
	v_fma_f32 v22, -v16, v21, v20
	v_fmac_f32_e32 v21, v22, v19
	v_fma_f32 v16, -v16, v21, v20
	v_div_fmas_f32 v16, v16, v19, v21
	v_div_fixup_f32 v15, v16, v15, v4
	v_div_scale_f32 v4, s[10:11], v14, v14, v18
	v_rcp_f32_e32 v16, v4
	s_nop 0
	v_fma_f32 v19, -v4, v16, 1.0
	v_fmac_f32_e32 v16, v19, v16
	v_div_scale_f32 v19, vcc, v18, v14, v18
	v_mul_f32_e32 v20, v19, v16
	v_fma_f32 v21, -v4, v20, v19
	v_fmac_f32_e32 v20, v21, v16
	v_fma_f32 v4, -v4, v20, v19
	v_div_fmas_f32 v4, v4, v16, v20
	v_div_fixup_f32 v14, v4, v14, v18
	v_pk_mul_f32 v[10:11], v[14:15], v[10:11]
	v_lshlrev_b32_e32 v16, 16, v17
	v_cvt_pk_bf16_f32 v4, v10, v11
	v_lshlrev_b32_e32 v10, 16, v5
	v_and_b32_e32 v11, 0xffff0000, v5
	v_and_b32_e32 v5, 0xffff0000, v17
	v_mul_f32_e32 v14, 0xbfb8aa3b, v16
	v_mul_f32_e32 v15, 0xbfb8aa3b, v5
	v_exp_f32_e32 v14, v14
	v_exp_f32_e32 v15, v15
	s_nop 0
	v_pk_add_f32 v[14:15], v[14:15], 1.0 op_sel_hi:[1,0]
	s_nop 0
	v_div_scale_f32 v17, s[10:11], v15, v15, v5
	v_rcp_f32_e32 v18, v17
	s_nop 0
	v_fma_f32 v19, -v17, v18, 1.0
	v_fmac_f32_e32 v18, v19, v18
	v_div_scale_f32 v19, vcc, v5, v15, v5
	v_mul_f32_e32 v20, v19, v18
	v_fma_f32 v21, -v17, v20, v19
	v_fmac_f32_e32 v20, v21, v18
	v_fma_f32 v17, -v17, v20, v19
	v_div_fmas_f32 v17, v17, v18, v20
	v_div_fixup_f32 v15, v17, v15, v5
	v_div_scale_f32 v5, s[10:11], v14, v14, v16
	v_rcp_f32_e32 v17, v5
	s_nop 0
	v_fma_f32 v18, -v5, v17, 1.0
	v_fmac_f32_e32 v17, v18, v17
	v_div_scale_f32 v18, vcc, v16, v14, v16
	v_mul_f32_e32 v19, v18, v17
	v_fma_f32 v20, -v5, v19, v18
	v_fmac_f32_e32 v19, v20, v17
	v_fma_f32 v5, -v5, v19, v18
	v_div_fmas_f32 v5, v5, v17, v19
	v_div_fixup_f32 v14, v5, v14, v16
	v_pk_mul_f32 v[10:11], v[14:15], v[10:11]
	s_nop 0
	v_cvt_pk_bf16_f32 v5, v10, v11
	v_add_co_u32_e32 v10, vcc, 0x373cb000, v12
	s_nop 1
	v_addc_co_u32_e32 v11, vcc, 0, v13, vcc
	global_store_dwordx4 v[10:11], v[2:5], off offset:1536
	s_waitcnt vmcnt(4)
	v_mov_b64_e32 v[98:99], v[114:115]
	v_mov_b64_e32 v[100:101], v[116:117]
	v_mov_b64_e32 v[102:103], v[118:119]
	v_mov_b64_e32 v[104:105], v[120:121]
	v_mov_b64_e32 v[106:107], v[122:123]
	v_mov_b64_e32 v[108:109], v[124:125]
	v_mov_b64_e32 v[110:111], v[126:127]
	v_mov_b64_e32 v[112:113], v[128:129]
	s_cbranch_scc0 .LBB0_41
	v_readlane_b32 s4, v254, 3
	s_add_i32 s6, s6, s4
	s_cmpk_gt_i32 s6, 0x4ff
	s_barrier
	s_cbranch_scc0 .LBB0_21
	v_readlane_b32 s0, v255, 62
	s_nop 3
	s_cmp_eq_u32 s0, 2
	s_cbranch_scc0 .LBB0_43
	s_mov_b32 s0, 0
	s_nop 0
	v_writelane_b32 v255, s0, 62
	s_branch .LBB0_94
